# c_phase: next unit's Q rows prefetched at epilogue start (conditional counted waits)
# speedup vs baseline: 1.0316x; 1.0037x over previous
; #define LAS __attribute__((address_space(3)))
; #define C_LOADP(p_) do { const bf16_t* q_ = (p_); rka = ldg16(q_ + kvlane); rva = ldg16(q_ + (size_t)16 * T * 64 + kvlane); rkb = ldg16(q_ + (size_t)T * 64 + kvlane); rvb = ldg16(q_ + (size_t)17 * T * 64 + kvlane); } while (0)
; __device__ __forceinline__ void c_phase(const bf16_t* Z, bf16_t* MIX, float* LSE, ldsp lds, int pi, int bx, int G, unsigned& gt, int wave0, int ucount) {
;     int tid_; asm volatile("v_mbcnt_lo_u32_b32 %0, -1, 0\n\tv_mbcnt_hi_u32_b32 %0, -1, %0" : "=&v"(tid_)); tid_ += wave0 * 64; const int tid = tid_, lane = tid & 63, w = __builtin_amdgcn_readfirstlane(tid >> 6), r32 = lane & 31, hi = lane >> 5;
;     const int hsel = w >> 2, gq = (w < 4) ? w : 7 - w, key = tid >> 3, ch = tid & 7;
;     const int ldil = 2 * pi, dil = 1 << ldil, lnb = 5 - ldil;
;     LAS float* wsf = (LAS float*)(lds + LDS_WSF) + w * 64;
;     const size_t tstride = (size_t)64 * dil * 64;
;     const unsigned kvlane = (unsigned)(key * dil * 64 + ch * 8), qlane = (unsigned)(r32 * dil * 64), olane = (unsigned)((lane >> 3) * dil * 1024 + (lane & 7) * 8), llane = (unsigned)(r32 * dil * 16);
;     ...
;     const u32x4 z4 = {0u, 0u, 0u, 0u};
;     u32x4 rka = z4, rva = z4, rkb = z4, rvb = z4;
;     const int per = (ucount + G - 1) / G, uend = (bx + 1) * per < ucount ? (bx + 1) * per : ucount;
;     int u = bx * per;
;     if (u >= uend) return;
;     {   C_DEC(u, b, hp, rs, blk); const int kt0 = blk >= 1 ? 2 * blk - 2 : 0; const bf16_t* kvp = C_KVP(b, hp, rs);
;         C_LOADP(kvp + kt0 * tstride);
;         { const ldsp b0 = lds + (gt & 1u) * 32768; tile_store(b0, rka, rva, key, ch); tile_store(b0 + 16384, rkb, rvb, key, ch); }
;         C_LOADP(kvp + (kt0 + 1) * tstride);
;         __syncthreads(); }
.LBB0_1032:
	s_mov_b64 s[0:1], s[90:91]
	v_mbcnt_lo_u32_b32 v18, -1, 0
	v_mbcnt_hi_u32_b32 v18, -1, v18
	s_andn2_b64 vcc, exec, s[66:67]
	v_add_u32_e32 v19, s93, v18
	s_nop 0
	v_readfirstlane_b32 s2, v19
	s_cbranch_vccnz .LBB0_1096
	s_add_u32 s4, s0, 0x200000
	s_addc_u32 s29, s1, 0
	s_add_u32 s5, s0, 0x4800000
	v_writelane_b32 v255, s5, 18
	s_addc_u32 s5, s1, 0
	s_add_u32 s80, s0, 0xc800000
	s_addc_u32 s81, s1, 0
	s_and_b32 s0, s2, 0x3fffffc0
	s_lshl_b32 s0, s0, 2
	v_writelane_b32 v255, s5, 19
	s_lshl_b32 s31, s38, 1
	s_add_i32 s5, s0, 0
	s_ashr_i32 s8, s2, 6
	s_ashr_i32 s30, s2, 8
	s_sub_i32 s33, 5, s31
	s_add_i32 s5, s5, 0x23000
	s_sub_i32 s0, 7, s8
	s_cmp_lt_i32 s8, 4
	s_cselect_b32 s2, s8, s0
	s_lshl_b32 s0, -1, s33
	v_readlane_b32 s28, v255, 6
	s_not_b32 s34, s0
	s_andn2_b32 s0, s28, s0
	s_ashr_i32 s1, s28, s33
	s_lshl_b32 s6, -1, s31
	v_readlane_b32 s12, v254, 18
	s_andn2_b32 s12, s1, s6
	s_lshl_b32 s1, s0, 1
	s_not_b32 s35, s6
	s_add_i32 s1, s1, -2
	s_cmp_lg_u32 s0, 0
	v_readlane_b32 s6, v255, 7
	v_readlane_b32 s13, v254, 19
	s_cselect_b32 s0, s1, 0
	v_readlane_b32 s7, v255, 8
	s_add_u32 s1, s80, s6
	s_addc_u32 s6, s81, s7
	s_lshl_b64 s[10:11], s[12:13], 7
	s_add_u32 s7, s1, s10
	s_addc_u32 s6, s6, s11
	s_mov_b32 s1, s13
	s_add_i32 s72, s31, 12
	v_ashrrev_i32_e32 v19, 3, v19
	v_and_b32_e32 v44, 7, v18
	s_lshl_b64 s[10:11], s[0:1], s72
	v_lshlrev_b32_e32 v20, s31, v19
	v_lshlrev_b32_e32 v21, 3, v44
	s_lshl_b64 s[10:11], s[10:11], 1
	v_lshl_or_b32 v184, v20, 6, v21
	s_add_u32 s10, s7, s10
	v_mov_b32_e32 v185, v177
	s_addc_u32 s11, s6, s11
	v_lshlrev_b64 v[36:37], 1, v[184:185]
	v_lshl_add_u64 v[32:33], s[10:11], 0, v[36:37]
	global_load_dwordx4 v[20:23], v[32:33], off
	s_mov_b32 s9, 0x800000
	v_add_co_u32_e32 v24, vcc, s9, v32
	s_mov_b32 s10, 0x80000
	s_nop 0
	v_addc_co_u32_e32 v25, vcc, 0, v33, vcc
	v_add_co_u32_e32 v28, vcc, s10, v32
	s_mov_b32 s11, 0x880000
	s_nop 0
	v_addc_co_u32_e32 v29, vcc, 0, v33, vcc
	global_load_dwordx4 v[24:27], v[24:25], off
	v_add_co_u32_e32 v32, vcc, s11, v32
	global_load_dwordx4 v[28:31], v[28:29], off
	s_nop 0
	v_addc_co_u32_e32 v33, vcc, 0, v33, vcc
	global_load_dwordx4 v[32:35], v[32:33], off
	s_lshl_b32 s1, s3, 15
	s_and_b32 s1, s1, 0x8000
	v_lshlrev_b32_e32 v202, 10, v44
	v_lshlrev_b32_e32 v44, 5, v44
	v_lshlrev_b32_e32 v45, 4, v19
	s_add_i32 s1, s1, 0
	v_xor_b32_e32 v203, v45, v44
	v_lshlrev_b32_e32 v19, 6, v19
	v_add3_u32 v44, s1, v202, v203
	v_and_b32_e32 v204, 0x1000, v202
	v_and_b32_e32 v205, 0xfffffc00, v19
	v_readlane_b32 s14, v254, 20
	v_readlane_b32 s15, v254, 21
	s_or_b32 s12, s0, 1
	v_readlane_b32 s16, v254, 22
	v_readlane_b32 s17, v254, 23
	v_readlane_b32 s18, v254, 24
	v_readlane_b32 s19, v254, 25
	v_readlane_b32 s20, v254, 26
	v_readlane_b32 s21, v254, 27
	v_readlane_b32 s22, v254, 28
	v_readlane_b32 s23, v254, 29
	v_readlane_b32 s24, v254, 30
	v_readlane_b32 s25, v254, 31
	v_readlane_b32 s26, v254, 32
	v_readlane_b32 s27, v254, 33
	v_and_b32_e32 v206, 0x3c0, v19
	v_lshlrev_b32_e32 v19, 4, v18
	v_and_b32_e32 v207, 48, v19
	v_and_b32_e32 v17, 31, v18
	v_and_b32_e32 v38, 63, v18
	v_lshlrev_b32_e32 v40, s31, v17
	v_bfe_u32 v43, v18, 5, 1
	v_lshlrev_b32_e32 v176, 7, v40
	v_writelane_b32 v255, s38, 20
	v_lshlrev_b32_e32 v186, 4, v43
	v_mov_b32_e32 v187, v177
	v_lshlrev_b32_e32 v41, 3, v18
	v_bfe_u32 v39, v18, 3, 3
	v_and_b32_e32 v42, 56, v41
	v_and_b32_e32 v250, 0xc0, v19
	v_lshlrev_b32_e32 v209, 2, v43
	v_lshlrev_b32_e32 v16, s31, v39
	v_or_b32_e32 v211, 1, v209
	v_lshl_or_b32 v16, v16, 10, v42
	v_lshlrev_b32_e32 v182, 4, v40
	v_mov_b32_e32 v183, v177
	v_or_b32_e32 v210, 32, v209
	v_or_b32_e32 v217, 33, v209
	v_or_b32_e32 v218, 2, v209
	v_or_b32_e32 v219, 34, v209
	v_or_b32_e32 v220, 3, v209
	v_or_b32_e32 v221, 35, v209
	v_or_b32_e32 v222, 8, v209
	v_or_b32_e32 v223, 40, v209
	v_or_b32_e32 v224, 9, v209
	v_or_b32_e32 v225, 41, v209
	v_or_b32_e32 v226, 10, v209
	v_or_b32_e32 v227, 42, v209
	v_or_b32_e32 v228, 11, v209
	v_or_b32_e32 v229, 43, v209
	s_waitcnt vmcnt(0)
	ds_write_b128 v44, v[20:23]
	v_add3_u32 v20, s1, v204, v205
	s_mov_b32 s1, s13
	v_writelane_b32 v254, s0, 18
	v_add3_u32 v20, v20, v206, v207
	ds_write_b128 v20, v[24:27] offset:8192
	ds_write_b128 v44, v[28:31] offset:16384
	ds_write_b128 v20, v[32:35] offset:24576
	v_writelane_b32 v254, s1, 19
	v_writelane_b32 v254, s2, 20
	v_writelane_b32 v254, s3, 21
	v_writelane_b32 v254, s4, 22
	v_writelane_b32 v254, s5, 23
	v_writelane_b32 v254, s6, 24
	v_writelane_b32 v254, s7, 25
	v_writelane_b32 v254, s8, 26
	v_writelane_b32 v254, s9, 27
	v_writelane_b32 v254, s10, 28
	v_writelane_b32 v254, s11, 29
	v_writelane_b32 v254, s12, 30
	v_writelane_b32 v254, s13, 31
	v_writelane_b32 v254, s14, 32
	v_writelane_b32 v254, s15, 33
	s_lshl_b64 s[0:1], s[12:13], s72
	s_lshl_b64 s[0:1], s[0:1], 1
	s_add_u32 s0, s7, s0
	s_addc_u32 s1, s6, s1
	v_lshl_add_u64 v[20:21], s[0:1], 0, v[36:37]
	v_add_co_u32_e32 v22, vcc, s9, v20
	global_load_dwordx4 v[128:131], v[20:21], off
	s_nop 0
	v_addc_co_u32_e32 v23, vcc, 0, v21, vcc
	global_load_dwordx4 v[132:135], v[22:23], off
	v_add_co_u32_e32 v22, vcc, s10, v20
	s_lshl_b32 s10, s2, 5
	s_nop 0
	v_addc_co_u32_e32 v23, vcc, 0, v21, vcc
	v_add_co_u32_e32 v20, vcc, s11, v20
	global_load_dwordx4 v[136:139], v[22:23], off
	s_nop 0
	v_addc_co_u32_e32 v21, vcc, 0, v21, vcc
	global_load_dwordx4 v[140:143], v[20:21], off
	s_cmp_lg_u32 s38, 0
	s_cselect_b64 s[82:83], -1, 0
	s_cmp_eq_u32 s38, 0
	s_cselect_b64 s[0:1], -1, 0
	v_writelane_b32 v254, s0, 36
	s_add_i32 s9, s31, 13
	s_lshl_b32 s2, 0x2000, s31
	v_writelane_b32 v254, s1, 37
	s_lshl_b32 s0, s30, 14
	s_add_i32 s94, s0, 0
	s_cmp_eq_u32 s38, 1
	v_cmp_gt_u32_e64 s[6:7], 32, v38
; #define C_LOADP(p_) do { const bf16_t* q_ = (p_); rka = ldg16(q_ + kvlane); rva = ldg16(q_ + (size_t)16 * T * 64 + kvlane); rkb = ldg16(q_ + (size_t)T * 64 + kvlane); rvb = ldg16(q_ + (size_t)17 * T * 64 + kvlane); } while (0)
; __device__ __forceinline__ void c_phase(const bf16_t* Z, bf16_t* MIX, float* LSE, ldsp lds, int pi, int bx, int G, unsigned& gt, int wave0, int ucount) {
;     ...
;     {   C_DEC(u, b, hp, rs, blk); const int kt0 = blk >= 1 ? 2 * blk - 2 : 0; const bf16_t* kvp = C_KVP(b, hp, rs);
;         C_LOADP(kvp + kt0 * tstride);
;         { const ldsp b0 = lds + (gt & 1u) * 32768; tile_store(b0, rka, rva, key, ch); tile_store(b0 + 16384, rkb, rvb, key, ch); }
;         C_LOADP(kvp + (kt0 + 1) * tstride);
;         __syncthreads(); }
;     for (; u < uend; ++u) {
;         C_DEC(u, b, hp, rs, blk);
;         const int head = 2 * hp + hsel, q0 = 128 * blk + 32 * gq, ql = q0 + r32;
;         const int kt0 = blk >= 1 ? 2 * blk - 2 : 0, kt1 = 2 * blk + 1;
;         const bf16_t* kvp = C_KVP(b, hp, rs);
;         const bool has_next = u + 1 < uend;
;         const int un = has_next ? u + 1 : u;
;         C_DEC(un, bn, hpn, rsn, blkn);
;         const int kt0n = blkn >= 1 ? 2 * blkn - 2 : 0;
;         const bf16_t* kvpn = C_KVP(bn, hpn, rsn) + kt0n * tstride;
;         bf16x8 qr[4]; q_load(qr, C_QROW(b, hp, rs, blk), hi);
	s_cselect_b64 s[0:1], -1, 0
	s_and_b64 s[0:1], s[0:1], s[6:7]
	v_lshl_add_u64 v[20:21], s[80:81], 0, v[176:177]
	v_writelane_b32 v255, s0, 21
	s_mulk_i32 s8, 0x2200
	v_lshl_add_u64 v[188:189], v[20:21], 0, v[186:187]
	v_lshlrev_b32_e32 v20, 4, v17
	v_writelane_b32 v255, s1, 22
	s_add_i32 s0, s8, 0
	v_bitop3_b32 v208, v20, v18, 32 bitop3:0x78
	v_lshlrev_b32_e32 v20, 2, v17
	v_lshlrev_b32_e32 v18, 1, v18
	s_add_i32 s0, s0, 0x10000
	v_and_b32_e32 v247, 32, v18
	v_add_u32_e32 v18, s0, v20
	v_lshl_add_u32 v19, v42, 2, s0
	s_lshl_b64 s[0:1], 1, s9
	v_writelane_b32 v255, s0, 23
	v_writelane_b32 v254, s30, 16
	v_add_u32_e32 v246, s5, v20
	v_writelane_b32 v255, s1, 24
	s_lshl_b64 s[0:1], 2, s9
	v_writelane_b32 v255, s0, 25
	v_mul_u32_u24_e32 v20, 0x440, v43
	v_mul_u32_u24_e32 v21, 0x110, v211
	v_writelane_b32 v255, s1, 26
	s_lshl_b64 s[0:1], 3, s9
	v_writelane_b32 v255, s0, 27
	v_mul_u32_u24_e32 v22, 0x110, v39
	v_lshlrev_b32_e32 v187, 10, v43
	v_writelane_b32 v255, s1, 28
	s_lshl_b64 s[0:1], 0x2000, s31
	v_writelane_b32 v254, s0, 38
	v_writelane_b32 v255, s29, 29
	v_writelane_b32 v255, s4, 30
	v_writelane_b32 v254, s1, 39
	s_lshl_b64 s[0:1], 0x4000, s31
	v_writelane_b32 v254, s0, 34
	v_writelane_b32 v255, s33, 31
	v_or_b32_e32 v230, 16, v209
	v_writelane_b32 v254, s1, 35
	v_writelane_b32 v254, s31, 40
	s_lshl_b64 s[0:1], 0x6000, s31
	v_writelane_b32 v254, s0, 0
	v_or_b32_e32 v231, 48, v209
	v_or_b32_e32 v232, 17, v209
	v_writelane_b32 v254, s1, 1
	s_add_i32 s0, s10, 0xffffff80
	v_or_b32_e32 v233, 49, v209
	v_or_b32_e32 v234, 18, v209
	v_or_b32_e32 v235, 50, v209
	v_or_b32_e32 v236, 19, v209
	v_or_b32_e32 v237, 51, v209
	v_or_b32_e32 v238, 24, v209
	v_or_b32_e32 v239, 56, v209
	v_or_b32_e32 v240, 25, v209
	v_or_b32_e32 v241, 57, v209
	v_or_b32_e32 v242, 26, v209
	v_or_b32_e32 v243, 58, v209
	v_or_b32_e32 v244, 27, v209
	v_or_b32_e32 v245, 59, v209
	v_and_b32_e32 v248, 24, v41
	v_lshlrev_b32_e32 v249, 8, v43
	v_lshl_add_u32 v251, v39, 2, s5
	v_writelane_b32 v254, s10, 41
	v_or_b32_e32 v252, s0, v17
	v_sub_u32_e32 v253, 0, v209
	v_lshlrev_b32_e32 v190, 1, v16
	v_add_u32_e32 v215, v18, v20
	v_add_u32_e32 v178, v18, v21
	v_add_u32_e32 v179, v19, v22
	s_mov_b32 s1, s28
	v_writelane_b32 v255, s35, 32
	s_waitcnt lgkmcnt(0)
	s_mov_b32 s101, 0
	s_barrier
.LBB0_1034:
	s_ashr_i32 s0, s1, s33
	v_readlane_b32 s36, v254, 18
	s_and_b32 s36, s0, s35
	s_lshr_b32 s0, s1, 4
	s_and_b32 s9, s1, s34
	s_and_b32 s0, s0, 14
	v_readlane_b32 s8, v254, 16
	s_add_i32 s14, s0, s8
	s_lshl_b32 s10, s9, 7
	v_readlane_b32 s8, v254, 41
	s_lshl_b32 s87, s9, 1
	s_ashr_i32 s12, s1, 8
	s_add_i32 s8, s10, s8
	s_add_i32 s11, s87, -2
	s_cmp_lg_u32 s9, 0
	s_cselect_b32 s84, s11, 0
	s_or_b32 s78, s87, 1
	s_add_i32 s86, s1, 1
	v_readlane_b32 s40, v254, 22
	v_readlane_b32 s41, v254, 23
	s_cmp_lt_i32 s86, s65
	s_mul_i32 s11, s12, 48
	s_cselect_b64 s[40:41], -1, 0
	s_cmp_ge_i32 s86, s65
	s_cselect_b64 s[92:93], -1, 0
	s_add_i32 s16, s14, s11
	s_ashr_i32 s9, s8, 31
	v_readlane_b32 s13, v254, 40
	s_ashr_i32 s17, s16, 31
	s_lshl_b64 s[18:19], s[8:9], s13
	s_add_u32 s18, s18, s36
	s_addc_u32 s19, s19, 0
	s_lshl_b64 s[16:17], s[16:17], 19
	s_lshl_b64 s[20:21], s[18:19], 7
	s_cmp_eq_u32 s101, 1
	s_mov_b32 s101, 0
	s_cbranch_scc1 .Lc_qskip
	v_lshl_add_u64 v[16:17], v[188:189], 0, s[16:17]
	v_lshl_add_u64 v[16:17], v[16:17], 0, s[20:21]
	global_load_dwordx4 v[160:163], v[16:17], off
	global_load_dwordx4 v[164:167], v[16:17], off offset:32
	global_load_dwordx4 v[168:171], v[16:17], off offset:64
	global_load_dwordx4 v[172:175], v[16:17], off offset:96
; #define GAS __attribute__((address_space(1)))
; __device__ __forceinline__ void c_phase(const bf16_t* Z, bf16_t* MIX, float* LSE, ldsp lds, int pi, int bx, int G, unsigned& gt, int wave0, int ucount) {
;     ...
;     for (; u < uend; ++u) {
;         C_DEC(u, b, hp, rs, blk);
;         const int head = 2 * hp + hsel, q0 = 128 * blk + 32 * gq, ql = q0 + r32;
;         const int kt0 = blk >= 1 ? 2 * blk - 2 : 0, kt1 = 2 * blk + 1;
;         const bf16_t* kvp = C_KVP(b, hp, rs);
;         const bool has_next = u + 1 < uend;
;         const int un = has_next ? u + 1 : u;
;         C_DEC(un, bn, hpn, rsn, blkn);
;         const int kt0n = blkn >= 1 ? 2 * blkn - 2 : 0;
;         const bf16_t* kvpn = C_KVP(bn, hpn, rsn) + kt0n * tstride;
;         bf16x8 qr[4]; q_load(qr, C_QROW(b, hp, rs, blk), hi);
;         GAS float* lsep = (GAS float*)(LSE + ((size_t)b * T + (size_t)q0 * dil + rs) * 16 + head + llane);
;         bf16_t* orow = MIX + ((size_t)b * T + (size_t)q0 * dil + rs) * 1024 + head * 64 + olane;
;         const size_t ostep = (size_t)8 * dil * 1024;
;         u32x4 orun[4] = {z4, z4, z4, z4}; float lse_old = 0.f;
;         float m = 0.f, l = 0.f; bool started = false;
;         f32x16 o[2], negm; splat16(negm, 0.f);
;         splat16(o[0], 0.f); splat16(o[1], 0.f);
.Lc_qskip:
	s_ashr_i32 s13, s12, 31
	s_lshl_b64 s[12:13], s[12:13], 12
	s_add_u32 s12, s18, s12
	s_addc_u32 s13, s19, s13
	s_lshl_b64 s[16:17], s[12:13], 6
	s_add_u32 s9, s4, s16
	s_addc_u32 s18, s29, s17
	s_ashr_i32 s15, s14, 31
	s_lshl_b64 s[16:17], s[14:15], 2
	s_add_u32 s16, s9, s16
	s_addc_u32 s17, s18, s17
	s_lshl_b64 s[12:13], s[12:13], 11
	v_readlane_b32 s9, v255, 18
	s_add_u32 s9, s9, s12
	v_readlane_b32 s12, v255, 19
	s_addc_u32 s15, s12, s13
	s_lshl_b32 s12, s14, 6
	s_ashr_i32 s13, s12, 31
	s_lshl_b64 s[12:13], s[12:13], 1
	s_add_u32 s12, s9, s12
	s_addc_u32 s13, s15, s13
	s_waitcnt vmcnt(12)
	v_mov_b32_e32 v191, v177
	v_mov_b64_e32 v[62:63], v[14:15]
	v_mov_b64_e32 v[46:47], v[14:15]
	v_mov_b64_e32 v[30:31], v[14:15]
	v_readlane_b32 s37, v254, 19
	v_lshl_add_u64 v[194:195], v[182:183], 2, s[16:17]
	v_lshl_add_u64 v[192:193], s[12:13], 0, v[190:191]
	v_mov_b64_e32 v[60:61], v[12:13]
	v_mov_b64_e32 v[58:59], v[10:11]
	v_mov_b64_e32 v[56:57], v[8:9]
	v_mov_b64_e32 v[54:55], v[6:7]
	v_mov_b64_e32 v[52:53], v[4:5]
	v_mov_b64_e32 v[50:51], v[2:3]
	v_mov_b64_e32 v[48:49], v[0:1]
	v_mov_b64_e32 v[44:45], v[12:13]
	v_mov_b64_e32 v[42:43], v[10:11]
	v_mov_b64_e32 v[40:41], v[8:9]
	v_mov_b64_e32 v[38:39], v[6:7]
	v_mov_b64_e32 v[36:37], v[4:5]
	v_mov_b64_e32 v[34:35], v[2:3]
	v_mov_b64_e32 v[32:33], v[0:1]
	v_mov_b64_e32 v[28:29], v[12:13]
	v_mov_b64_e32 v[26:27], v[10:11]
	v_mov_b64_e32 v[24:25], v[8:9]
	v_mov_b64_e32 v[22:23], v[6:7]
	v_mov_b64_e32 v[20:21], v[4:5]
	v_mov_b64_e32 v[18:19], v[2:3]
	v_mov_b64_e32 v[16:17], v[0:1]
	s_ashr_i32 s98, s86, 8
	s_mul_i32 s98, s98, 48
	s_lshr_b32 s99, s86, 4
	s_and_b32 s99, s99, 14
	s_add_i32 s98, s98, s99
	v_readlane_b32 s99, v254, 16
	s_nop 0
	s_add_i32 s98, s98, s99
	s_lshl_b32 s98, s98, 12
	s_and_b32 s99, s86, s34
	s_lshl_b32 s99, s99, 7
	v_readlane_b32 s100, v254, 41
	s_nop 0
	s_add_i32 s99, s99, s100
	v_readlane_b32 s100, v254, 40
	s_nop 0
	s_lshl_b32 s99, s99, s100
	s_ashr_i32 s100, s86, s33
	s_and_b32 s100, s100, s35
	s_add_i32 s99, s99, s100
	s_add_i32 s98, s98, s99
	s_lshl_b32 s98, s98, 7
	s_cmp_gt_i32 s84, s78
	v_readlane_b32 s38, v254, 20
	v_readlane_b32 s39, v254, 21
	v_readlane_b32 s42, v254, 24
	v_readlane_b32 s43, v254, 25
	v_readlane_b32 s44, v254, 26
	v_readlane_b32 s45, v254, 27
	v_readlane_b32 s46, v254, 28
	v_readlane_b32 s47, v254, 29
	v_readlane_b32 s48, v254, 30
	v_readlane_b32 s49, v254, 31
	v_readlane_b32 s50, v254, 32
	v_readlane_b32 s51, v254, 33
	s_cbranch_scc1 .LBB0_1074
	s_add_i32 s0, s11, s0
	s_add_i32 s12, s0, 16
	s_ashr_i32 s13, s12, 31
	s_lshl_b64 s[12:13], s[12:13], 19
	s_add_u32 s0, s80, s12
	s_addc_u32 s9, s81, s13
	s_lshl_b64 s[12:13], s[36:37], 7
	s_add_u32 s85, s0, s12
	s_addc_u32 s0, s9, s13
	s_and_b64 s[12:13], s[40:41], exec
	s_cselect_b32 s1, s86, s1
	s_ashr_i32 s9, s1, 8
	s_lshr_b32 s11, s1, 4
	s_mul_i32 s9, s9, 48
	s_and_b32 s11, s11, 14
	s_or_b32 s9, s9, s11
	s_add_i32 s12, s9, 16
	s_ashr_i32 s13, s12, 31
	s_lshl_b64 s[12:13], s[12:13], 19
	s_add_u32 s9, s80, s12
	s_addc_u32 s11, s81, s13
	s_ashr_i32 s12, s1, s33
	s_and_b32 s12, s12, s35
	s_lshl_b32 s12, s12, 7
	s_add_u32 s9, s9, s12
	s_addc_u32 s11, s11, 0
	s_and_b32 s1, s1, s34
	s_lshl_b32 s12, s1, 1
	s_add_i32 s12, s12, -2
	s_mov_b32 s4, s65
	s_cmp_lg_u32 s1, 0
	s_mov_b32 s1, s37
	s_cselect_b32 s36, s12, 0
	v_writelane_b32 v254, s0, 18
	s_waitcnt vmcnt(8)
	v_mov_b32_e32 v144, 0
	s_mov_b32 s95, s34
	v_writelane_b32 v254, s1, 19
	v_writelane_b32 v254, s2, 20
	v_writelane_b32 v254, s3, 21
	v_writelane_b32 v254, s4, 22
	v_writelane_b32 v254, s5, 23
	v_writelane_b32 v254, s6, 24
	v_writelane_b32 v254, s7, 25
	v_writelane_b32 v254, s8, 26
	v_writelane_b32 v254, s9, 27
	v_writelane_b32 v254, s10, 28
	v_writelane_b32 v254, s11, 29
	v_writelane_b32 v254, s12, 30
	v_writelane_b32 v254, s13, 31
	v_writelane_b32 v254, s14, 32
	v_writelane_b32 v254, s15, 33
	s_lshl_b64 s[12:13], s[36:37], s72
	s_lshl_b64 s[12:13], s[12:13], 1
	s_add_u32 s1, s9, s12
	s_addc_u32 s74, s11, s13
	s_or_b32 s75, s8, 31
	s_add_i32 s76, s8, 0xffffff80
	v_readlane_b32 s8, v255, 23
	v_readlane_b32 s9, v255, 24
	v_add_u32_e32 v64, s10, v252
	s_lshl_b32 s73, s84, 6
	v_lshl_add_u64 v[196:197], s[8:9], 1, v[192:193]
	v_readlane_b32 s8, v255, 25
	v_readlane_b32 s9, v255, 26
	s_lshl_b32 s77, s3, 15
	v_subrev_u32_e32 v213, s73, v64
	v_lshl_add_u64 v[198:199], s[8:9], 1, v[192:193]
	v_readlane_b32 s8, v255, 27
	v_readlane_b32 s9, v255, 28
	s_mov_b64 s[88:89], 0
	v_mov_b32_e32 v191, 0
	v_lshl_add_u64 v[200:201], s[8:9], 1, v[192:193]
	v_mov_b32_e32 v181, 0
	v_mov_b32_e32 v180, 0
	v_mov_b32_e32 v145, v144
	v_mov_b32_e32 v146, v144
	v_mov_b32_e32 v147, v144
	v_mov_b32_e32 v148, v144
	v_mov_b32_e32 v149, v144
	v_mov_b32_e32 v150, v144
	v_mov_b32_e32 v151, v144
	v_mov_b32_e32 v152, v144
	v_mov_b32_e32 v153, v144
	v_mov_b32_e32 v154, v144
	v_mov_b32_e32 v155, v144
	v_mov_b32_e32 v156, v144
	v_mov_b32_e32 v157, v144
	v_mov_b32_e32 v158, v144
	v_mov_b32_e32 v159, v144
	s_waitcnt vmcnt(0)

; __device__ __forceinline__ void c_phase(const bf16_t* Z, bf16_t* MIX, float* LSE, ldsp lds, int pi, int bx, int G, unsigned& gt, int wave0, int ucount) {
;     ...
;         const bool has_next = u + 1 < uend;
;         const int un = has_next ? u + 1 : u;
;         C_DEC(un, bn, hpn, rsn, blkn);
;         const int kt0n = blkn >= 1 ? 2 * blkn - 2 : 0;
;         const bf16_t* kvpn = C_KVP(bn, hpn, rsn) + kt0n * tstride;
;         bf16x8 qr[4]; q_load(qr, C_QROW(b, hp, rs, blk), hi);
.LBB0_1076:
	s_and_b64 vcc, exec, s[40:41]
	s_cbranch_vccz .Lc_qpre_skip
	s_mov_b32 s99, 0
	v_lshl_add_u64 v[64:65], v[188:189], 0, s[98:99]
	global_load_dwordx4 v[160:163], v[64:65], off
	global_load_dwordx4 v[164:167], v[64:65], off offset:32
	global_load_dwordx4 v[168:171], v[64:65], off offset:64
	global_load_dwordx4 v[172:175], v[64:65], off offset:96
	s_mov_b32 s101, 1

; __device__ __forceinline__ float fexp2(float x) { return __builtin_amdgcn_exp2f(x); }
; __device__ __forceinline__ float xh_sum(float v) { auto rr = __builtin_amdgcn_permlane32_swap(__float_as_uint(v), __float_as_uint(v), false, false); return __uint_as_float(rr[0]) + __uint_as_float(rr[1]); }
; __device__ __forceinline__ void c_phase(const bf16_t* Z, bf16_t* MIX, float* LSE, ldsp lds, int pi, int bx, int G, unsigned& gt, int wave0, int ucount) {
;     ...
;         const float lt = xh_sum(l), lse = m + __log2f(lt);
;         float wa = 0.f, wb = 1.0f / lt;
;         if (pi > 0) {
;             const float mx = fmaxf(lse_old, lse), nl = mx + __log2f(fexp2(lse_old - mx) + fexp2(lse - mx));
;             wa = fexp2(lse_old - nl); wb = fexp2(lse - nl) / lt;
;             if (pi < 2 && hi == 0) *lsep = nl;
;         } else if (hi == 0) *lsep = lse;
.LBB0_1079:
	v_add_f32_e32 v48, v181, v48
	v_log_f32_e32 v49, v48
	s_andn2_b64 vcc, exec, s[10:11]
	v_add_f32_e32 v51, v180, v49
	s_cbranch_vccnz .LBB0_1081
	v_max_f32_e32 v49, v51, v51
	s_and_b64 vcc, exec, s[40:41]
	s_cbranch_vccnz .Lc_wA_deep
	s_waitcnt vmcnt(4)
	s_branch .Lc_wA_join
.Lc_wA_deep:
	s_waitcnt vmcnt(8)
.Lc_wA_join:
	v_max_f32_e32 v50, v191, v191
	v_max_f32_e32 v49, v50, v49
	v_sub_f32_e32 v50, v191, v49
	v_sub_f32_e32 v52, v51, v49
	v_exp_f32_e32 v50, v50
	v_exp_f32_e32 v52, v52
	s_andn2_b64 s[0:1], s[8:9], exec
	v_readlane_b32 s8, v255, 21
	v_readlane_b32 s9, v255, 22
	v_add_f32_e32 v50, v50, v52
	v_log_f32_e32 v50, v50
	s_and_b64 s[8:9], s[8:9], exec
	s_or_b64 s[8:9], s[0:1], s[8:9]
	v_add_f32_e32 v52, v49, v50
	v_sub_f32_e32 v49, v191, v52
	v_sub_f32_e32 v50, v51, v52
	v_exp_f32_e32 v49, v49
	v_exp_f32_e32 v50, v50
	v_mov_b32_e32 v51, v52
	s_and_saveexec_b64 s[10:11], s[8:9]
	s_cbranch_execnz .LBB0_1082
	s_branch .LBB0_1083

; #define LAS __attribute__((address_space(3)))
; #define LDS_WAIT() asm volatile("s_waitcnt lgkmcnt(0)" ::: "memory")
; __device__ __forceinline__ int crow(int r, int hi) { return (r & 3) + 8 * (r >> 2) + 4 * hi; }
; __device__ __forceinline__ void c_phase(const bf16_t* Z, bf16_t* MIX, float* LSE, ldsp lds, int pi, int bx, int G, unsigned& gt, int wave0, int ucount) {
;     ...
;         LDS_WAIT();
;         if (hi == 0) { wsf[r32] = wa; wsf[32 + r32] = wb; }
;         LDS_WAIT();
;         LAS float* stg = (LAS float*)(lds + 65536 + w * 8704);
; #pragma unroll
;         for (int d0 = 0; d0 < 2; ++d0)
; #pragma unroll
;             for (int r = 0; r < 16; ++r) { const int q = crow(r, hi); stg[q * 68 + d0 * 32 + r32] = wsf[32 + q] * o[d0][r]; }
;         LDS_WAIT();
; #pragma unroll
;         for (int i = 0; i < 4; ++i) {
;             const int row = i * 8 + (lane >> 3);
;             const f32x4 x0 = *(const LAS f32x4*)(stg + row * 68 + (lane & 7) * 8), x1 = *(const LAS f32x4*)(stg + row * 68 + (lane & 7) * 8 + 4);
;             float v[8] = {x0[0], x0[1], x0[2], x0[3], x1[0], x1[1], x1[2], x1[3]};
;             if (pi > 0) { const float fa = wsf[row];
; #pragma unroll
;                 for (int k = 0; k < 4; ++k) { const unsigned wd = orun[i][k]; v[2 * k] += fa * __builtin_bit_cast(float, wd << 16); v[2 * k + 1] += fa * __builtin_bit_cast(float, wd & 0xffff0000u); } }
.LBB0_1085:
	s_or_b64 exec, exec, s[8:9]
	s_waitcnt lgkmcnt(0)
	v_add_u32_e32 v48, s5, v186
	s_andn2_b64 vcc, exec, s[82:83]
	ds_read_b128 v[52:55], v48 offset:128
	ds_read_b128 v[56:59], v48 offset:160
	ds_read_b128 v[60:63], v48 offset:192
	ds_read_b128 v[48:51], v48 offset:224
	s_waitcnt lgkmcnt(3)
	v_mul_f32_e32 v32, v32, v52
	v_mul_f32_e32 v33, v33, v53
	v_mul_f32_e32 v34, v34, v54
	v_mul_f32_e32 v35, v35, v55
	v_mul_f32_e32 v16, v16, v52
	v_mul_f32_e32 v17, v17, v53
	v_mul_f32_e32 v18, v18, v54
	v_mul_f32_e32 v19, v19, v55
	s_waitcnt lgkmcnt(2)
	v_mul_f32_e32 v36, v36, v56
	v_mul_f32_e32 v37, v37, v57
	v_mul_f32_e32 v38, v38, v58
	v_mul_f32_e32 v39, v39, v59
	v_mul_f32_e32 v20, v20, v56
	v_mul_f32_e32 v21, v21, v57
	v_mul_f32_e32 v22, v22, v58
	v_mul_f32_e32 v23, v23, v59
	s_waitcnt lgkmcnt(1)
	v_mul_f32_e32 v40, v40, v60
	v_mul_f32_e32 v41, v41, v61
	v_mul_f32_e32 v42, v42, v62
	v_mul_f32_e32 v43, v43, v63
	v_mul_f32_e32 v24, v24, v60
	v_mul_f32_e32 v25, v25, v61
	v_mul_f32_e32 v26, v26, v62
	v_mul_f32_e32 v27, v27, v63
	s_waitcnt lgkmcnt(0)
	v_mul_f32_e32 v44, v44, v48
	v_mul_f32_e32 v45, v45, v49
	v_mul_f32_e32 v46, v46, v50
	v_mul_f32_e32 v47, v47, v51
	v_mul_f32_e32 v28, v28, v48
	v_mul_f32_e32 v29, v29, v49
	v_mul_f32_e32 v30, v30, v50
	v_mul_f32_e32 v31, v31, v51
	ds_write_b32 v215, v32
	ds_write_b32 v178, v33
	ds_write_b32 v178, v34 offset:272
	ds_write_b32 v178, v35 offset:544
	ds_write_b32 v178, v36 offset:1904
	ds_write_b32 v178, v37 offset:2176
	ds_write_b32 v178, v38 offset:2448
	ds_write_b32 v178, v39 offset:2720
	ds_write_b32 v178, v40 offset:4080
	ds_write_b32 v178, v41 offset:4352
	ds_write_b32 v178, v42 offset:4624
	ds_write_b32 v178, v43 offset:4896
	s_waitcnt lgkmcnt(6)
	ds_write_b32 v178, v44 offset:6256
	ds_write_b32 v178, v45 offset:6528
	ds_write_b32 v178, v46 offset:6800
	ds_write_b32 v178, v47 offset:7072
	ds_write_b32 v215, v16 offset:128
	ds_write_b32 v178, v17 offset:128
	ds_write_b32 v178, v18 offset:400
	ds_write_b32 v178, v19 offset:672
	s_waitcnt lgkmcnt(6)
	ds_write_b32 v178, v20 offset:2032
	ds_write_b32 v178, v21 offset:2304
	ds_write_b32 v178, v22 offset:2576
	ds_write_b32 v178, v23 offset:2848
	ds_write_b32 v178, v24 offset:4208
	ds_write_b32 v178, v25 offset:4480
	ds_write_b32 v178, v26 offset:4752
	ds_write_b32 v178, v27 offset:5024
	s_waitcnt lgkmcnt(6)
	ds_write_b32 v178, v28 offset:6384
	ds_write_b32 v178, v29 offset:6656
	ds_write_b32 v178, v30 offset:6928
	ds_write_b32 v178, v31 offset:7200
	v_cndmask_b32_e64 v24, 0, 1, s[82:83]
	v_cmp_ne_u32_e64 s[8:9], 1, v24
	s_waitcnt lgkmcnt(0)
	ds_read_b128 v[20:23], v179
	ds_read_b128 v[16:19], v179 offset:16
	s_cbranch_vccnz .LBB0_1087
	ds_read_b32 v24, v251
	s_and_b64 vcc, exec, s[40:41]
	s_cbranch_vccnz .Lc_wB_deep
	s_waitcnt vmcnt(3)
	s_branch .Lc_wB_join

; #define LAS __attribute__((address_space(3)))
; __device__ __forceinline__ unsigned pk2(float lo, float hi) { f32x2_t v = {lo, hi}; bf16x2_t b = __builtin_convertvector(v, bf16x2_t); return __builtin_bit_cast(unsigned, b); }
; #define GAS __attribute__((address_space(1)))
; __device__ __forceinline__ void c_phase(const bf16_t* Z, bf16_t* MIX, float* LSE, ldsp lds, int pi, int bx, int G, unsigned& gt, int wave0, int ucount) {
;     ...
; #pragma unroll
;         for (int i = 0; i < 4; ++i) {
;             const int row = i * 8 + (lane >> 3);
;             const f32x4 x0 = *(const LAS f32x4*)(stg + row * 68 + (lane & 7) * 8), x1 = *(const LAS f32x4*)(stg + row * 68 + (lane & 7) * 8 + 4);
;             float v[8] = {x0[0], x0[1], x0[2], x0[3], x1[0], x1[1], x1[2], x1[3]};
;             if (pi > 0) { const float fa = wsf[row];
; #pragma unroll
;                 for (int k = 0; k < 4; ++k) { const unsigned wd = orun[i][k]; v[2 * k] += fa * __builtin_bit_cast(float, wd << 16); v[2 * k + 1] += fa * __builtin_bit_cast(float, wd & 0xffff0000u); } }
;             u32x4 ow; ow.x = pk2(v[0], v[1]); ow.y = pk2(v[2], v[3]); ow.z = pk2(v[4], v[5]); ow.w = pk2(v[6], v[7]);
;             *(GAS u32x4*)(orow + i * ostep) = ow;
.Lc_wB_join:
	v_lshlrev_b32_e32 v26, 16, v156
	v_and_b32_e32 v27, 0xffff0000, v156
	s_waitcnt lgkmcnt(0)
	v_pk_fma_f32 v[20:21], v[24:25], v[26:27], v[20:21] op_sel_hi:[0,1,1]
	v_lshlrev_b32_e32 v26, 16, v157
	v_and_b32_e32 v27, 0xffff0000, v157
	v_pk_fma_f32 v[22:23], v[24:25], v[26:27], v[22:23] op_sel_hi:[0,1,1]
	v_lshlrev_b32_e32 v26, 16, v158
	v_and_b32_e32 v27, 0xffff0000, v158
	v_pk_fma_f32 v[16:17], v[24:25], v[26:27], v[16:17] op_sel_hi:[0,1,1]
	v_lshlrev_b32_e32 v26, 16, v159
	v_and_b32_e32 v27, 0xffff0000, v159
	v_pk_fma_f32 v[18:19], v[24:25], v[26:27], v[18:19] op_sel_hi:[0,1,1]
.LBB0_1087:
	s_waitcnt lgkmcnt(1)
	v_cvt_pk_bf16_f32 v20, v20, v21
	v_cvt_pk_bf16_f32 v21, v22, v23
	s_waitcnt lgkmcnt(0)
	v_cvt_pk_bf16_f32 v22, v16, v17
	v_cvt_pk_bf16_f32 v23, v18, v19
	global_store_dwordx4 v[192:193], v[20:23], off
	ds_read_b128 v[20:23], v179 offset:2176
	ds_read_b128 v[16:19], v179 offset:2192
	s_and_b64 vcc, exec, s[8:9]
	s_cbranch_vccnz .LBB0_1089
	ds_read_b32 v24, v251 offset:32
	s_and_b64 vcc, exec, s[40:41]
	s_cbranch_vccnz .Lc_wC_deep
	s_waitcnt vmcnt(3)
	s_branch .Lc_wC_join

; #define LAS __attribute__((address_space(3)))
; __device__ __forceinline__ unsigned pk2(float lo, float hi) { f32x2_t v = {lo, hi}; bf16x2_t b = __builtin_convertvector(v, bf16x2_t); return __builtin_bit_cast(unsigned, b); }
; #define GAS __attribute__((address_space(1)))
; __device__ __forceinline__ void c_phase(const bf16_t* Z, bf16_t* MIX, float* LSE, ldsp lds, int pi, int bx, int G, unsigned& gt, int wave0, int ucount) {
;     ...
; #pragma unroll
;         for (int i = 0; i < 4; ++i) {
;             const int row = i * 8 + (lane >> 3);
;             const f32x4 x0 = *(const LAS f32x4*)(stg + row * 68 + (lane & 7) * 8), x1 = *(const LAS f32x4*)(stg + row * 68 + (lane & 7) * 8 + 4);
;             float v[8] = {x0[0], x0[1], x0[2], x0[3], x1[0], x1[1], x1[2], x1[3]};
;             if (pi > 0) { const float fa = wsf[row];
; #pragma unroll
;                 for (int k = 0; k < 4; ++k) { const unsigned wd = orun[i][k]; v[2 * k] += fa * __builtin_bit_cast(float, wd << 16); v[2 * k + 1] += fa * __builtin_bit_cast(float, wd & 0xffff0000u); } }
;             u32x4 ow; ow.x = pk2(v[0], v[1]); ow.y = pk2(v[2], v[3]); ow.z = pk2(v[4], v[5]); ow.w = pk2(v[6], v[7]);
;             *(GAS u32x4*)(orow + i * ostep) = ow;
.Lc_wC_join:
	v_lshlrev_b32_e32 v26, 16, v152
	v_and_b32_e32 v27, 0xffff0000, v152
	s_waitcnt lgkmcnt(0)
	v_pk_fma_f32 v[20:21], v[24:25], v[26:27], v[20:21] op_sel_hi:[0,1,1]
	v_lshlrev_b32_e32 v26, 16, v153
	v_and_b32_e32 v27, 0xffff0000, v153
	v_pk_fma_f32 v[22:23], v[24:25], v[26:27], v[22:23] op_sel_hi:[0,1,1]
	v_lshlrev_b32_e32 v26, 16, v154
	v_and_b32_e32 v27, 0xffff0000, v154
	v_pk_fma_f32 v[16:17], v[24:25], v[26:27], v[16:17] op_sel_hi:[0,1,1]
	v_lshlrev_b32_e32 v26, 16, v155
	v_and_b32_e32 v27, 0xffff0000, v155
	v_pk_fma_f32 v[18:19], v[24:25], v[26:27], v[18:19] op_sel_hi:[0,1,1]
.LBB0_1089:
	v_readlane_b32 s0, v254, 38
	v_readlane_b32 s1, v254, 39
	s_waitcnt lgkmcnt(1)
	v_cvt_pk_bf16_f32 v20, v20, v21
	v_cvt_pk_bf16_f32 v21, v22, v23
	s_waitcnt lgkmcnt(0)
	v_cvt_pk_bf16_f32 v22, v16, v17
	v_cvt_pk_bf16_f32 v23, v18, v19
	v_lshl_add_u64 v[16:17], s[0:1], 1, v[192:193]
	global_store_dwordx4 v[16:17], v[20:23], off
	ds_read_b128 v[20:23], v179 offset:4352
	ds_read_b128 v[16:19], v179 offset:4368
	s_and_b64 vcc, exec, s[8:9]
	s_cbranch_vccnz .LBB0_1091
	ds_read_b32 v24, v251 offset:64
	s_and_b64 vcc, exec, s[40:41]
	s_cbranch_vccnz .Lc_wD_deep
	s_waitcnt vmcnt(3)
	s_branch .Lc_wD_join

; #define LAS __attribute__((address_space(3)))
; __device__ __forceinline__ unsigned pk2(float lo, float hi) { f32x2_t v = {lo, hi}; bf16x2_t b = __builtin_convertvector(v, bf16x2_t); return __builtin_bit_cast(unsigned, b); }
; #define GAS __attribute__((address_space(1)))
; __device__ __forceinline__ void c_phase(const bf16_t* Z, bf16_t* MIX, float* LSE, ldsp lds, int pi, int bx, int G, unsigned& gt, int wave0, int ucount) {
;     ...
; #pragma unroll
;         for (int i = 0; i < 4; ++i) {
;             const int row = i * 8 + (lane >> 3);
;             const f32x4 x0 = *(const LAS f32x4*)(stg + row * 68 + (lane & 7) * 8), x1 = *(const LAS f32x4*)(stg + row * 68 + (lane & 7) * 8 + 4);
;             float v[8] = {x0[0], x0[1], x0[2], x0[3], x1[0], x1[1], x1[2], x1[3]};
;             if (pi > 0) { const float fa = wsf[row];
; #pragma unroll
;                 for (int k = 0; k < 4; ++k) { const unsigned wd = orun[i][k]; v[2 * k] += fa * __builtin_bit_cast(float, wd << 16); v[2 * k + 1] += fa * __builtin_bit_cast(float, wd & 0xffff0000u); } }
;             u32x4 ow; ow.x = pk2(v[0], v[1]); ow.y = pk2(v[2], v[3]); ow.z = pk2(v[4], v[5]); ow.w = pk2(v[6], v[7]);
;             *(GAS u32x4*)(orow + i * ostep) = ow;
.Lc_wD_join:
	v_lshlrev_b32_e32 v26, 16, v148
	v_and_b32_e32 v27, 0xffff0000, v148
	s_waitcnt lgkmcnt(0)
	v_pk_fma_f32 v[20:21], v[24:25], v[26:27], v[20:21] op_sel_hi:[0,1,1]
	v_lshlrev_b32_e32 v26, 16, v149
	v_and_b32_e32 v27, 0xffff0000, v149
	v_pk_fma_f32 v[22:23], v[24:25], v[26:27], v[22:23] op_sel_hi:[0,1,1]
	v_lshlrev_b32_e32 v26, 16, v150
	v_and_b32_e32 v27, 0xffff0000, v150
	v_pk_fma_f32 v[16:17], v[24:25], v[26:27], v[16:17] op_sel_hi:[0,1,1]
	v_lshlrev_b32_e32 v26, 16, v151
	v_and_b32_e32 v27, 0xffff0000, v151
	v_pk_fma_f32 v[18:19], v[24:25], v[26:27], v[18:19] op_sel_hi:[0,1,1]
.LBB0_1091:
	v_readlane_b32 s0, v254, 34
	v_readlane_b32 s1, v254, 35
	s_waitcnt lgkmcnt(1)
	v_cvt_pk_bf16_f32 v20, v20, v21
	v_cvt_pk_bf16_f32 v21, v22, v23
	s_waitcnt lgkmcnt(0)
	v_cvt_pk_bf16_f32 v22, v16, v17
	v_cvt_pk_bf16_f32 v23, v18, v19
	v_lshl_add_u64 v[16:17], s[0:1], 1, v[192:193]
	global_store_dwordx4 v[16:17], v[20:23], off
	ds_read_b128 v[20:23], v179 offset:6528
	ds_read_b128 v[16:19], v179 offset:6544
	s_and_b64 vcc, exec, s[8:9]
	s_cbranch_vccnz .LBB0_1093
	ds_read_b32 v24, v251 offset:96
	s_and_b64 vcc, exec, s[40:41]
	s_cbranch_vccnz .Lc_wE_deep
	s_waitcnt vmcnt(3)
	s_branch .Lc_wE_join

; #define LAS __attribute__((address_space(3)))
; __device__ __forceinline__ unsigned pk2(float lo, float hi) { f32x2_t v = {lo, hi}; bf16x2_t b = __builtin_convertvector(v, bf16x2_t); return __builtin_bit_cast(unsigned, b); }
; #define GAS __attribute__((address_space(1)))
; __device__ __forceinline__ void c_phase(const bf16_t* Z, bf16_t* MIX, float* LSE, ldsp lds, int pi, int bx, int G, unsigned& gt, int wave0, int ucount) {
;     ...
; #pragma unroll
;         for (int i = 0; i < 4; ++i) {
;             const int row = i * 8 + (lane >> 3);
;             const f32x4 x0 = *(const LAS f32x4*)(stg + row * 68 + (lane & 7) * 8), x1 = *(const LAS f32x4*)(stg + row * 68 + (lane & 7) * 8 + 4);
;             float v[8] = {x0[0], x0[1], x0[2], x0[3], x1[0], x1[1], x1[2], x1[3]};
;             if (pi > 0) { const float fa = wsf[row];
; #pragma unroll
;                 for (int k = 0; k < 4; ++k) { const unsigned wd = orun[i][k]; v[2 * k] += fa * __builtin_bit_cast(float, wd << 16); v[2 * k + 1] += fa * __builtin_bit_cast(float, wd & 0xffff0000u); } }
;             u32x4 ow; ow.x = pk2(v[0], v[1]); ow.y = pk2(v[2], v[3]); ow.z = pk2(v[4], v[5]); ow.w = pk2(v[6], v[7]);
;             *(GAS u32x4*)(orow + i * ostep) = ow;
.Lc_wE_join:
	v_lshlrev_b32_e32 v26, 16, v144
	v_and_b32_e32 v27, 0xffff0000, v144
	s_waitcnt lgkmcnt(0)
	v_pk_fma_f32 v[20:21], v[24:25], v[26:27], v[20:21] op_sel_hi:[0,1,1]
	v_lshlrev_b32_e32 v26, 16, v145
	v_and_b32_e32 v27, 0xffff0000, v145
	v_pk_fma_f32 v[22:23], v[24:25], v[26:27], v[22:23] op_sel_hi:[0,1,1]
	v_lshlrev_b32_e32 v26, 16, v146
	v_and_b32_e32 v27, 0xffff0000, v146
	v_pk_fma_f32 v[16:17], v[24:25], v[26:27], v[16:17] op_sel_hi:[0,1,1]
	v_lshlrev_b32_e32 v26, 16, v147
	v_and_b32_e32 v27, 0xffff0000, v147
	v_pk_fma_f32 v[18:19], v[24:25], v[26:27], v[18:19] op_sel_hi:[0,1,1]
